# attention: LDS-DMA requests spread through each wave's interval (softmax VALU gaps / P.V MFMA shadow) instead of one group
# speedup vs baseline: 1.0154x; 1.0027x over previous
; __device__ __forceinline__ int v_st(int k, int c) { const int kk = (k & ~0xC) | ((k & 4) << 1) | ((k & 8) >> 1); return ((kk >> 3) * 4 + (c >> 5)) * 512 + ((kk & 7) * 32 + (c & 31)) * 2; }
; __device__ __forceinline__ int v_rd_base(int lane) { return ((lane & 3) << 3) | (((lane >> 2) & 3) << 6) | (((lane >> 4) & 1) << 5) | (((lane >> 5) & 1) << 8); }
; #define KLOAD(k0) do { ks0 = *reinterpret_cast<const bf16x8*>(&Kh[(long)((k0) + sr) * LDK + sc]); ks1 = *reinterpret_cast<const bf16x8*>(&Kh[(long)((k0) + 32 + sr) * LDK + sc]); } while (0)
; #define KWRITE(b) do { const int kc = sc * 2; *(bf16x8*)(K_lds + (b) * 16384 + KSWZ(sr, kc)) = ks0; *(bf16x8*)(K_lds + (b) * 16384 + KSWZ(32 + sr, kc)) = ks1; } while (0)
; template <int LDQ, int LDK, int LDO>
; __device__ __forceinline__ void attn_pair_body(const bf16* __restrict__ Qb, const bf16* __restrict__ Kh, const bf16* __restrict__ Vh, float* __restrict__ Ob, int NT, char* lds, int tid_in) {
;   int tid_l = tid_in; asm volatile("" : "+v"(tid_l)); const int tid = tid_l, wid = __builtin_amdgcn_readfirstlane(tid >> 6), lane = tid & 63, r32 = lane & 31, hi = lane >> 5;
;   const int rg = wid & 3, vhw = wid >> 2;
;   char* V_lds = lds + AP_V; char* K_lds = lds + AP_K;
;   char* Pp = lds + AP_P + rg * 8192;
;   float* ALp = (float*)(lds + AP_AL) + rg * 64; float* Mp = (float*)(lds + AP_M) + rg * 32; unsigned* FLp = (unsigned*)(lds + AP_FL) + rg * 2; float* LXp = (float*)(lds + AP_LX) + rg * 64;
;   float m_reg = -1e30f, l_reg = 0.f; f32x16 o[4] = {}; bf16x8 qr[8];
;   const bf16* Qw = Qb + (long)(rg * QBLK + r32) * LDQ + hi * 8;
; #pragma unroll
;   for (int d0 = 0; d0 < 8; ++d0) qr[d0] = *reinterpret_cast<const bf16x8*>(Qw + d0 * 16);
;   const int sr = tid >> 4, sc = (tid & 15) * 8, vst0 = v_st(sr, sc), vst1 = v_st(32 + sr, sc);
;   const int vb0 = (int)(uintptr_t)(V_lds + vhw * 16384) + v_rd_base(lane);
;   bf16x8 ks0, ks1, vs00, vs01, vs10, vs11;
;     ...
;   KLOAD(0); asm volatile("s_waitcnt vmcnt(0)" ::: "memory"); KWRITE(0);
;   if (NT > 1) { KLOAD(KVBLK); asm volatile("s_waitcnt vmcnt(0)" ::: "memory"); KWRITE(1); }
;   if (NT > 2) KLOAD(2 * KVBLK);
;   VLOAD(0);
;   __syncthreads();
;   f32x16 p0 = f32x16{}, p1 = f32x16{};
;   if (vhw == 0) { qkt_batched(p0, p1, (const bf16*)K_lds, qr, r32, hi); }
;   __syncthreads();
.LBB0_1015:
	v_and_b32_e32 v5, 0xfffff0, v188
	v_lshlrev_b32_e32 v7, 1, v188
	v_and_or_b32 v5, v7, 8, v5
	v_lshrrev_b32_e32 v7, 1, v188
	v_lshrrev_b32_e32 v5, 1, v5
	v_lshrrev_b32_e32 v8, 5, v15
	v_and_b32_e32 v9, 3, v188
	s_lshl_b32 s10, s10, 2
	v_or_b32_e32 v5, v5, v8
	v_and_or_b32 v7, v7, 4, v9
	s_add_i32 s10, s10, 0
	v_lshlrev_b32_e32 v5, 9, v5
	v_lshlrev_b32_e32 v7, 6, v7
	v_and_b32_e32 v9, 48, v4
	s_add_i32 s12, s10, 0x20400
	s_lshl_b32 s10, s5, 8
	v_or3_b32 v201, v5, v7, v9
	v_and_b32_e32 v5, 0xfffff0, v189
	v_lshlrev_b32_e32 v10, 1, v189
	s_add_i32 s10, s10, 0
	v_and_or_b32 v5, v10, 8, v5
	s_lshl_b32 s9, s5, 13
	s_add_i32 s28, s10, 0x20000
	s_lshl_b32 s10, s5, 3
	v_lshrrev_b32_e32 v5, 1, v5
	v_and_b32_e32 v6, 63, v14
	s_ashr_i32 s8, s8, 8
	s_add_i32 s9, s9, 0
	s_add_i32 s10, s10, 0
	v_or_b32_e32 v5, v5, v8
	s_ashr_i32 s19, s18, 31
	s_add_i32 s15, s9, 0x18000
	s_lshl_b32 s9, s5, 6
	s_add_i32 s10, s10, 0x20600
	v_lshlrev_b32_e32 v5, 9, v5
	s_lshl_b32 s13, s8, 14
	v_lshlrev_b32_e32 v203, 4, v6
	v_or3_b32 v202, v5, v7, v9
	s_cmp_lg_u32 0, -1
	v_lshlrev_b32_e32 v5, 3, v6
	v_and_b32_e32 v7, 0xc0, v203
	v_lshlrev_b32_e32 v8, 1, v6
	s_cselect_b32 s14, 0, 0
	v_and_or_b32 v7, v5, 24, v7
	v_and_b32_e32 v8, 32, v8
	v_and_b32_e32 v5, 0x100, v5
	s_add_i32 s14, s14, s13
	v_or3_b32 v5, v7, v8, v5
	v_add_u32_e32 v211, s14, v5
	v_mov_b32_e32 v5, v3
	v_lshl_add_u64 v[182:183], s[20:21], 0, v[4:5]
	s_mov_b64 s[60:61], s[20:21]
	s_lshl_b32 s20, s8, 7
	v_lshlrev_b32_e32 v180, 2, v187
	s_add_i32 s14, s28, s20
	v_mov_b32_e32 v18, v3
	v_mov_b32_e32 v19, v3
	v_lshl_add_u64 v[184:185], s[38:39], 0, v[4:5]
	s_mov_b64 s[68:69], s[38:39]
	v_cmp_gt_u32_e64 s[38:39], 32, v6
	v_cmp_eq_u32_e64 s[40:41], 0, v6
	s_lshl_b32 s13, s8, 12
	v_add_u32_e32 v213, s14, v180
	s_lshl_b32 s14, s8, 2
	v_mov_b32_e32 v4, v3
	v_mov_b32_e32 v6, v3
	v_mov_b32_e32 v7, v3
	v_mov_b32_e32 v8, v3
	v_mov_b32_e32 v9, v3
	v_mov_b32_e32 v10, v3
	v_mov_b32_e32 v11, v3
	v_mov_b32_e32 v12, v3
	v_mov_b32_e32 v13, v3
	v_mov_b32_e32 v14, v3
	v_mov_b32_e32 v15, v3
	v_mov_b32_e32 v16, v3
	v_mov_b32_e32 v17, v3
	v_mov_b64_e32 v[66:67], v[18:19]
	v_mov_b64_e32 v[50:51], v[18:19]
	v_mov_b64_e32 v[34:35], v[18:19]
	s_mov_b32 s11, 1
	v_add_u32_e32 v212, s12, v180
	s_add_i32 s12, s4, -1
	s_add_i32 s13, s15, s13
	s_add_i32 s14, s10, s14
	v_add_u32_e32 v214, s28, v180
	v_add_u32_e32 v215, s28, v2
	v_add_u32_e32 v216, s15, v203
	v_mov_b32_e32 v218, 0
	v_mov_b32_e32 v217, 0xf149f2ca
	v_mov_b64_e32 v[64:65], v[16:17]
	v_mov_b64_e32 v[62:63], v[14:15]
	v_mov_b64_e32 v[60:61], v[12:13]
	v_mov_b64_e32 v[58:59], v[10:11]
	v_mov_b64_e32 v[56:57], v[8:9]
	v_mov_b64_e32 v[54:55], v[6:7]
	v_mov_b64_e32 v[52:53], v[4:5]
	v_mov_b64_e32 v[48:49], v[16:17]
	v_mov_b64_e32 v[46:47], v[14:15]
	v_mov_b64_e32 v[44:45], v[12:13]
	v_mov_b64_e32 v[42:43], v[10:11]
	v_mov_b64_e32 v[40:41], v[8:9]
	v_mov_b64_e32 v[38:39], v[6:7]
	v_mov_b64_e32 v[36:37], v[4:5]
	v_mov_b64_e32 v[32:33], v[16:17]
	v_mov_b64_e32 v[30:31], v[14:15]
	v_mov_b64_e32 v[28:29], v[12:13]
	v_mov_b64_e32 v[26:27], v[10:11]
	v_mov_b64_e32 v[24:25], v[8:9]
	v_mov_b64_e32 v[22:23], v[6:7]
	v_mov_b64_e32 v[20:21], v[4:5]
	v_readfirstlane_b32 s46, v186
	s_lshr_b32 s46, s46, 6
	s_lshl_b32 s32, s46, 11
	s_add_i32 s32, s32, 0x10000
	s_lshr_b32 s47, s46, 2
	s_and_b32 s29, s46, 3
	s_lshl_b32 s58, s47, 14
	s_lshl_b32 s28, s29, 12
	s_add_i32 s58, s58, s28
	v_and_b32_e32 v132, 15, v186
	v_bfe_u32 v133, v186, 4, 2
	v_xor_b32_e32 v134, v132, v133
	v_lshlrev_b32_e32 v134, 4, v134
	v_mul_u32_u24_e32 v135, 0x2400, v133
	s_mul_i32 s28, s46, 0x12000
	v_add3_u32 v172, v134, v135, s28
	v_xor_b32_e32 v134, 64, v134
	v_add3_u32 v173, v134, v135, s28
	v_add_u32_e32 v173, 0x9000, v173
	v_bfe_u32 v132, v186, 4, 1
	v_bfe_u32 v133, v186, 2, 2
	v_lshl_add_u32 v132, v132, 3, v133
	v_mul_u32_u24_e32 v132, 0x2400, v132
	v_bfe_u32 v133, v186, 5, 1
	v_lshlrev_b32_e32 v133, 6, v133
	v_and_b32_e32 v134, 3, v186
	v_lshl_add_u32 v133, v134, 4, v133
	s_mul_i32 s28, s29, 0x24000
	s_lshl_b32 s47, s47, 8
	s_add_i32 s28, s28, s47
	v_add3_u32 v174, v132, v133, s28
	s_add_u32 s74, s60, 0x90000
	s_addc_u32 s75, s61, 0
	s_sub_u32 s92, s68, 0x90000
	s_subb_u32 s93, s69, 0
	s_sub_u32 s96, s68, 0x87000
	s_subb_u32 s97, s69, 0
	s_add_i32 s65, s32, 0x4000
	s_add_i32 s77, s58, 0x8000
	s_barrier
	s_branch .LBB0_1017

; #define SBAR() __builtin_amdgcn_sched_barrier(0)
; __device__ __forceinline__ void partialSM(f32x16& p0, f32x16& p1, float& m_reg, float& mn, float& alpha) {
;   constexpr float C = SCALE * 1.4426950408889634f;
;   float pmax = p0[0]; for (int r = 1; r < 16; ++r) pmax = fmaxf(pmax, p0[r]); for (int r = 0; r < 16; ++r) pmax = fmaxf(pmax, p1[r]);
;   { auto rr = __builtin_amdgcn_permlane32_swap(__float_as_uint(pmax), __float_as_uint(pmax), false, false);
;     pmax = fmaxf(__uint_as_float(rr[0]), __uint_as_float(rr[1])); }
;   if (__builtin_expect(__all(pmax - m_reg <= THR / SCALE), 1)) { mn = m_reg; alpha = 1.f; }
;   else { mn = fmaxf(m_reg, pmax); alpha = __builtin_amdgcn_exp2f((m_reg - mn) * C); m_reg = mn; }
;   float mnC = -mn * C;
;   for (int r = 0; r < 16; ++r) p0[r] = fmaf(p0[r], C, mnC); for (int r = 0; r < 16; ++r) p1[r] = fmaf(p1[r], C, mnC);
; template <int LDQ, int LDK, int LDO>
; __device__ __forceinline__ void attn_pair_body(const bf16* __restrict__ Qb, const bf16* __restrict__ Kh, const bf16* __restrict__ Vh, float* __restrict__ Ob, int NT, char* lds, int tid_in) {
;     ...
;     const float alp_v = ALp[pb * 32 + r32], m_v = Mp[r32];
;     const bf16x8 a0 = *reinterpret_cast<const bf16x8*>(Pp + pb * 4096 + 0 * 1024 + lane * 16), a1 = *reinterpret_cast<const bf16x8*>(Pp + pb * 4096 + 1 * 1024 + lane * 16);
;     const bf16x8 a2 = *reinterpret_cast<const bf16x8*>(Pp + pb * 4096 + 2 * 1024 + lane * 16), a3 = *reinterpret_cast<const bf16x8*>(Pp + pb * 4096 + 3 * 1024 + lane * 16);
;     SBAR();
;     KWRITE(b);
;     VWRITE(b);
;     { const int tk = j + 3 < NT ? j + 3 : NT - 1, tv = j + 1 < NT ? j + 1 : NT - 1; KLOAD(tk * KVBLK); VLOAD(tv * KVBLK); }
;     SBAR();
;     if (prod) {
;       if (flp) l_reg *= alp_v;
;       if (j >= 1) m_reg = m_v;
;       float mn, al; bf16x8 pa0, pa1, pa2, pa3;
;       partialSM(p0, p1, m_reg, mn, al);
;       finishSM(p0, p1, al, l_reg, pa0, pa1, pa2, pa3);
;       *reinterpret_cast<bf16x8*>(Pp + b * 4096 + 0 * 1024 + lane * 16) = pa0; *reinterpret_cast<bf16x8*>(Pp + b * 4096 + 1 * 1024 + lane * 16) = pa1;
;       *reinterpret_cast<bf16x8*>(Pp + b * 4096 + 2 * 1024 + lane * 16) = pa2; *reinterpret_cast<bf16x8*>(Pp + b * 4096 + 3 * 1024 + lane * 16) = pa3;
;       if (hi == 0) { ALp[b * 32 + r32] = al; Mp[r32] = m_reg; }
;       const unsigned fl = __any(al < 1.f) ? 1u : 0u;
;       if (lane == 0) FLp[b] = fl;
.LBB0_1023:
	v_lshl_add_u32 v156, s21, 7, v214
	v_lshl_add_u32 v157, s21, 12, v216
	ds_read_b32 v219, v156
	ds_read_b128 v[168:171], v157
	ds_read_b32 v220, v212
	ds_read_b128 v[164:167], v157 offset:1024
	ds_read_b128 v[160:163], v157 offset:2048
	ds_read_b128 v[156:159], v157 offset:3072
	s_and_b64 vcc, exec, s[42:43]
	s_cbranch_vccnz .Lpa_cons
	v_lshl_add_u32 v176, s21, 15, v211
	ds_read_b64_tr_b16 v[132:133], v176 offset:0
	ds_read_b64_tr_b16 v[134:135], v176 offset:0x800
	ds_read_b64_tr_b16 v[136:137], v176 offset:0x1000
	ds_read_b64_tr_b16 v[138:139], v176 offset:0x1800
	ds_read_b64_tr_b16 v[140:141], v176 offset:0x2000
	ds_read_b64_tr_b16 v[142:143], v176 offset:0x2800
	ds_read_b64_tr_b16 v[144:145], v176 offset:0x3000
	ds_read_b64_tr_b16 v[146:147], v176 offset:0x3800
	s_xor_b32 s65, s65, 0x4000
	s_xor_b32 s77, s77, 0x8000
	s_add_u32 s74, s74, 0x90000
	s_addc_u32 s75, s75, 0
	s_add_u32 s92, s92, 0x90000
	s_addc_u32 s93, s93, 0
	s_add_u32 s96, s96, 0x90000
	s_addc_u32 s97, s97, 0
	s_mov_b32 m0, s65
	v_max_f32_e32 v176, v85, v85
	v_max_f32_e32 v177, v84, v84
	global_load_lds_dwordx4 v172, s[74:75]
	s_add_i32 m0, s65, 0x400
	v_max_f32_e32 v176, v177, v176
	v_max3_f32 v176, v176, v86, v87
	v_max3_f32 v176, v176, v88, v89
	v_max3_f32 v176, v176, v90, v91
	v_max3_f32 v176, v176, v92, v93
	v_max3_f32 v176, v176, v94, v95
	v_max3_f32 v176, v176, v96, v97
	v_max3_f32 v176, v176, v98, v99
	global_load_lds_dwordx4 v173, s[74:75]
	s_mov_b32 m0, s77
	v_max3_f32 v176, v176, v68, v69
	v_max3_f32 v176, v176, v70, v71
	v_max3_f32 v176, v176, v72, v73
	v_max3_f32 v176, v176, v74, v75
	v_max3_f32 v176, v176, v76, v77
	v_max3_f32 v176, v176, v78, v79
	v_max3_f32 v176, v176, v80, v81
	v_max3_f32 v176, v176, v82, v83
	global_load_lds_dwordx4 v174, s[92:93]
	s_add_i32 m0, s77, 0x380
	v_mov_b32_e32 v177, v176
	s_nop 1
	v_permlane32_swap_b32_e32 v176, v177
	v_max_f32_e32 v177, v177, v177
	v_max_f32_e32 v176, v176, v176
	s_waitcnt lgkmcnt(11)
	v_readfirstlane_b32 s29, v210
	s_cmp_lg_u32 s29, 0
	s_cselect_b64 s[62:63], -1, 0
	s_and_b64 s[62:63], s[62:63], s[56:57]
	v_cndmask_b32_e64 v217, v220, v217, s[44:45]
	v_max_f32_e32 v221, v176, v177
	v_sub_f32_e32 v176, v221, v217
	v_cmp_ge_f32_e32 vcc, s27, v176
	s_cmp_eq_u64 vcc, exec
	v_mov_b32_e32 v220, 1.0
	s_cbranch_scc0 .LBB0_1036
.LBB0_1025:
	v_mul_f32_e32 v176, 0xbe0293ee, v217
	v_fmamk_f32 v84, v84, 0x3e0293ee, v176
	v_fmamk_f32 v85, v85, 0x3e0293ee, v176
	v_exp_f32_e32 v84, v84
	v_fmamk_f32 v86, v86, 0x3e0293ee, v176
	v_exp_f32_e32 v85, v85
	v_fmamk_f32 v87, v87, 0x3e0293ee, v176
	v_exp_f32_e32 v86, v86
	v_fmamk_f32 v88, v88, 0x3e0293ee, v176
	v_fmamk_f32 v89, v89, 0x3e0293ee, v176
	v_fmamk_f32 v90, v90, 0x3e0293ee, v176
	v_fmamk_f32 v91, v91, 0x3e0293ee, v176
	v_fmamk_f32 v92, v92, 0x3e0293ee, v176
	global_load_lds_dwordx4 v174, s[92:93] offset:128
	s_add_i32 m0, s77, 0x800
	v_fmamk_f32 v93, v93, 0x3e0293ee, v176
	v_fmamk_f32 v94, v94, 0x3e0293ee, v176
	v_fmamk_f32 v95, v95, 0x3e0293ee, v176
	v_fmamk_f32 v96, v96, 0x3e0293ee, v176
	v_fmamk_f32 v97, v97, 0x3e0293ee, v176
	v_fmamk_f32 v98, v98, 0x3e0293ee, v176
	v_fmamk_f32 v99, v99, 0x3e0293ee, v176
	v_fmamk_f32 v68, v68, 0x3e0293ee, v176
	v_fmamk_f32 v69, v69, 0x3e0293ee, v176
	v_fmamk_f32 v70, v70, 0x3e0293ee, v176
	v_fmamk_f32 v71, v71, 0x3e0293ee, v176
	v_fmamk_f32 v72, v72, 0x3e0293ee, v176
	v_fmamk_f32 v73, v73, 0x3e0293ee, v176
	v_fmamk_f32 v74, v74, 0x3e0293ee, v176
	global_load_lds_dwordx4 v174, s[96:97]
	s_add_i32 m0, s77, 0xb80
	v_fmamk_f32 v75, v75, 0x3e0293ee, v176
	v_fmamk_f32 v76, v76, 0x3e0293ee, v176
	v_fmamk_f32 v77, v77, 0x3e0293ee, v176
	v_fmamk_f32 v78, v78, 0x3e0293ee, v176
	v_fmamk_f32 v79, v79, 0x3e0293ee, v176
	v_fmamk_f32 v80, v80, 0x3e0293ee, v176
	v_fmamk_f32 v81, v81, 0x3e0293ee, v176
	v_fmamk_f32 v82, v82, 0x3e0293ee, v176
	v_fmac_f32_e32 v176, 0x3e0293ee, v83
	v_exp_f32_e32 v87, v87
	v_exp_f32_e32 v88, v88
	v_exp_f32_e32 v83, v176
	v_add_f32_e32 v176, 0, v84
	v_exp_f32_e32 v89, v89
	v_add_f32_e32 v176, v85, v176
	v_exp_f32_e32 v90, v90
	global_load_lds_dwordx4 v174, s[96:97] offset:128
	v_add_f32_e32 v176, v86, v176
	v_exp_f32_e32 v91, v91
	v_add_f32_e32 v176, v87, v176
	v_exp_f32_e32 v92, v92
	v_add_f32_e32 v176, v88, v176
	v_exp_f32_e32 v93, v93
	v_add_f32_e32 v176, v89, v176
	v_exp_f32_e32 v94, v94
	v_add_f32_e32 v176, v90, v176
	v_exp_f32_e32 v95, v95
	v_add_f32_e32 v176, v91, v176
	v_exp_f32_e32 v96, v96
	v_add_f32_e32 v176, v92, v176
	v_exp_f32_e32 v97, v97
	v_add_f32_e32 v176, v93, v176
	v_exp_f32_e32 v98, v98
	v_add_f32_e32 v176, v94, v176
	v_exp_f32_e32 v99, v99
	v_add_f32_e32 v176, v95, v176
	v_exp_f32_e32 v68, v68
	v_add_f32_e32 v176, v96, v176
	v_exp_f32_e32 v69, v69
	v_add_f32_e32 v176, v97, v176
	v_exp_f32_e32 v70, v70
	v_add_f32_e32 v176, v98, v176
	v_exp_f32_e32 v71, v71
	v_add_f32_e32 v176, v99, v176
	v_exp_f32_e32 v72, v72
	v_add_f32_e32 v176, v68, v176
	v_exp_f32_e32 v73, v73
	v_add_f32_e32 v176, v69, v176
	v_exp_f32_e32 v74, v74
	v_add_f32_e32 v176, v70, v176
	v_exp_f32_e32 v75, v75
	v_add_f32_e32 v176, v71, v176
	v_exp_f32_e32 v76, v76
	v_add_f32_e32 v176, v72, v176
	v_exp_f32_e32 v77, v77
	v_add_f32_e32 v176, v73, v176
	v_exp_f32_e32 v78, v78
	v_add_f32_e32 v176, v74, v176
	v_exp_f32_e32 v79, v79
	v_add_f32_e32 v176, v75, v176
	v_exp_f32_e32 v80, v80
	v_add_f32_e32 v176, v76, v176
	v_exp_f32_e32 v81, v81
	v_add_f32_e32 v176, v77, v176
	v_exp_f32_e32 v82, v82
	v_add_f32_e32 v176, v78, v176
	v_add_f32_e32 v176, v79, v176
	v_add_f32_e32 v176, v80, v176
	v_add_f32_e32 v176, v81, v176
	v_add_f32_e32 v176, v82, v176
	v_add_f32_e32 v221, v83, v176
	v_mov_b32_e32 v222, v221
	v_cvt_pk_bf16_f32 v224, v84, v85
	v_cvt_pk_bf16_f32 v225, v86, v87
	v_cvt_pk_bf16_f32 v226, v88, v89
	v_cvt_pk_bf16_f32 v227, v90, v91
	s_nop 1
	v_permlane32_swap_b32_e32 v221, v222
	v_permlane32_swap_b32_e32 v224, v226
	v_permlane32_swap_b32_e32 v225, v227
	v_cvt_pk_bf16_f32 v234, v92, v93
	v_cvt_pk_bf16_f32 v235, v94, v95
	v_cvt_pk_bf16_f32 v236, v96, v97
	v_cvt_pk_bf16_f32 v237, v98, v99
	v_cvt_pk_bf16_f32 v238, v68, v69
	v_cvt_pk_bf16_f32 v239, v70, v71
	v_cvt_pk_bf16_f32 v240, v72, v73
	v_cvt_pk_bf16_f32 v241, v74, v75
	v_cvt_pk_bf16_f32 v242, v76, v77
	v_cvt_pk_bf16_f32 v243, v78, v79
	v_cvt_pk_bf16_f32 v244, v80, v81
	v_cvt_pk_bf16_f32 v245, v82, v83
	v_add_u32_e32 v176, s13, v203
	v_permlane32_swap_b32_e32 v234, v236
	v_permlane32_swap_b32_e32 v235, v237
	v_permlane32_swap_b32_e32 v238, v240
	v_permlane32_swap_b32_e32 v239, v241
	v_permlane32_swap_b32_e32 v242, v244
	v_permlane32_swap_b32_e32 v243, v245
	ds_write_b128 v176, v[224:227]
	ds_write_b128 v176, v[234:237] offset:1024
	ds_write_b128 v176, v[238:241] offset:2048
	ds_write_b128 v176, v[242:245] offset:3072
	s_and_saveexec_b64 s[42:43], s[38:39]
	s_cbranch_execz .LBB0_1027
	ds_write_b32 v213, v220
	ds_write_b32 v212, v217

; #define SBAR() __builtin_amdgcn_sched_barrier(0)
; #define TRD(Lb, Hb, D0) Lb[0] = tr_read<v_rd_off(D0, 0, 0)>(vb); Hb[0] = tr_read<v_rd_off(D0, 0, 1)>(vb); Lb[1] = tr_read<v_rd_off(D0, 1, 0)>(vb); Hb[1] = tr_read<v_rd_off(D0, 1, 1)>(vb); \
;     Lb[2] = tr_read<v_rd_off(D0, 2, 0)>(vb); Hb[2] = tr_read<v_rd_off(D0, 2, 1)>(vb); Lb[3] = tr_read<v_rd_off(D0, 3, 0)>(vb); Hb[3] = tr_read<v_rd_off(D0, 3, 1)>(vb);
; #define MM(D0, Lb, Hb) o[D0] = __builtin_amdgcn_mfma_f32_32x32x16_bf16(pa0, PK(Lb[0], Hb[0]), o[D0], 0, 0, 0); o[D0] = __builtin_amdgcn_mfma_f32_32x32x16_bf16(pa1, PK(Lb[1], Hb[1]), o[D0], 0, 0, 0); \
;     o[D0] = __builtin_amdgcn_mfma_f32_32x32x16_bf16(pa2, PK(Lb[2], Hb[2]), o[D0], 0, 0, 0); o[D0] = __builtin_amdgcn_mfma_f32_32x32x16_bf16(pa3, PK(Lb[3], Hb[3]), o[D0], 0, 0, 0);
; #define KLOAD(k0) do { ks0 = *reinterpret_cast<const bf16x8*>(&Kh[(long)((k0) + sr) * LDK + sc]); ks1 = *reinterpret_cast<const bf16x8*>(&Kh[(long)((k0) + 32 + sr) * LDK + sc]); } while (0)
; #define VLOAD(k0) do { vs00 = *reinterpret_cast<const bf16x8*>(&Vh[(long)((k0) + sr) * LDK + sc]); vs01 = *reinterpret_cast<const bf16x8*>(&Vh[(long)((k0) + 32 + sr) * LDK + sc]); \
;     vs10 = *reinterpret_cast<const bf16x8*>(&Vh[(long)((k0) + sr) * LDK + 128 + sc]); vs11 = *reinterpret_cast<const bf16x8*>(&Vh[(long)((k0) + 32 + sr) * LDK + 128 + sc]); } while (0)
; __device__ __forceinline__ void pv_batched(f32x16* o, int vb, bf16x8 pa0, bf16x8 pa1, bf16x8 pa2, bf16x8 pa3) {
;   s16x4 L0[4], H0[4], L1[4], H1[4];
;     ...
;   TRD(L0, H0, 0) SBAR(); TRD(L1, H1, 1) SBAR();
;   asm volatile("s_waitcnt lgkmcnt(8)" ::: "memory"); SBAR();
;   MM(0, L0, H0) SBAR();
;   TRD(L0, H0, 2) SBAR();
;   asm volatile("s_waitcnt lgkmcnt(8)" ::: "memory"); SBAR();
;   MM(1, L1, H1) SBAR();
;   TRD(L1, H1, 3) SBAR();
;   asm volatile("s_waitcnt lgkmcnt(8)" ::: "memory"); SBAR();
;   MM(2, L0, H0) SBAR();
;   asm volatile("s_waitcnt lgkmcnt(0)" ::: "memory"); SBAR();
;   MM(3, L1, H1) SBAR();
; template <int LDQ, int LDK, int LDO>
; __device__ __forceinline__ void attn_pair_body(const bf16* __restrict__ Qb, const bf16* __restrict__ Kh, const bf16* __restrict__ Vh, float* __restrict__ Ob, int NT, char* lds, int tid_in) {
;     ...
;     KWRITE(b);
;     VWRITE(b);
;     { const int tk = j + 3 < NT ? j + 3 : NT - 1, tv = j + 1 < NT ? j + 1 : NT - 1; KLOAD(tk * KVBLK); VLOAD(tv * KVBLK); }
.Lpa_cons_pv:
	v_lshl_add_u32 v219, s21, 15, v211
	ds_read_b64_tr_b16 v[220:221], v219 offset:0
	ds_read_b64_tr_b16 v[222:223], v219 offset:0x800
	ds_read_b64_tr_b16 v[224:225], v219 offset:0x1000
	ds_read_b64_tr_b16 v[226:227], v219 offset:0x1800
	ds_read_b64_tr_b16 v[234:235], v219 offset:0x2000
	ds_read_b64_tr_b16 v[236:237], v219 offset:0x2800
	ds_read_b64_tr_b16 v[238:239], v219 offset:0x3000
	ds_read_b64_tr_b16 v[240:241], v219 offset:0x3800
	ds_read_b64_tr_b16 v[242:243], v219 offset:0x200
	ds_read_b64_tr_b16 v[244:245], v219 offset:0xa00
	ds_read_b64_tr_b16 v[246:247], v219 offset:0x1200
	ds_read_b64_tr_b16 v[248:249], v219 offset:0x1a00
	ds_read_b64_tr_b16 v[176:177], v219 offset:0x2200
	ds_read_b64_tr_b16 v[178:179], v219 offset:0x2a00
	ds_read_b64_tr_b16 v[228:229], v219 offset:0x3200
	ds_read_b64_tr_b16 v[230:231], v219 offset:0x3a00
	s_xor_b32 s65, s65, 0x4000
	s_xor_b32 s77, s77, 0x8000
	s_add_u32 s74, s74, 0x90000
	s_addc_u32 s75, s75, 0
	s_add_u32 s92, s92, 0x90000
	s_addc_u32 s93, s93, 0
	s_add_u32 s96, s96, 0x90000
	s_addc_u32 s97, s97, 0
	s_mov_b32 m0, s65
	s_waitcnt lgkmcnt(8)
	s_nop 0
	v_mfma_f32_32x32x16_bf16 v[4:19], v[168:171], v[220:223], v[4:19]
	global_load_lds_dwordx4 v172, s[74:75]
	s_add_i32 m0, s65, 0x400
	s_waitcnt lgkmcnt(8)
	v_mfma_f32_32x32x16_bf16 v[4:19], v[164:167], v[224:227], v[4:19]
	s_waitcnt lgkmcnt(7)
	v_mfma_f32_32x32x16_bf16 v[4:19], v[160:163], v[234:237], v[4:19]
	global_load_lds_dwordx4 v173, s[74:75]
	s_mov_b32 m0, s77
	s_waitcnt lgkmcnt(6)
	v_mfma_f32_32x32x16_bf16 v[4:19], v[156:159], v[238:241], v[4:19]
	ds_read_b64_tr_b16 v[220:221], v219 offset:0x400
	ds_read_b64_tr_b16 v[222:223], v219 offset:0xc00
	ds_read_b64_tr_b16 v[224:225], v219 offset:0x1400
	ds_read_b64_tr_b16 v[226:227], v219 offset:0x1c00
	ds_read_b64_tr_b16 v[232:233], v219 offset:0x2400
	ds_read_b64_tr_b16 v[234:235], v219 offset:0x2c00
	ds_read_b64_tr_b16 v[236:237], v219 offset:0x3400
	ds_read_b64_tr_b16 v[238:239], v219 offset:0x3c00
	s_waitcnt lgkmcnt(8)
	v_mfma_f32_32x32x16_bf16 v[52:67], v[168:171], v[242:245], v[52:67]
	global_load_lds_dwordx4 v174, s[92:93]
	s_add_i32 m0, s77, 0x380
	v_mfma_f32_32x32x16_bf16 v[52:67], v[164:167], v[246:249], v[52:67]
	v_mfma_f32_32x32x16_bf16 v[52:67], v[160:163], v[176:179], v[52:67]
	global_load_lds_dwordx4 v174, s[92:93] offset:128
	s_add_i32 m0, s77, 0x800
	v_mfma_f32_32x32x16_bf16 v[52:67], v[156:159], v[228:231], v[52:67]
	ds_read_b64_tr_b16 v[176:177], v219 offset:0x600
	ds_read_b64_tr_b16 v[178:179], v219 offset:0xe00
	ds_read_b64_tr_b16 v[228:229], v219 offset:0x1600
	ds_read_b64_tr_b16 v[230:231], v219 offset:0x1e00
	ds_read_b64_tr_b16 v[240:241], v219 offset:0x2600
	ds_read_b64_tr_b16 v[242:243], v219 offset:0x2e00
	ds_read_b64_tr_b16 v[244:245], v219 offset:0x3600
	ds_read_b64_tr_b16 v[246:247], v219 offset:0x3e00
	s_waitcnt lgkmcnt(8)
	v_mfma_f32_32x32x16_bf16 v[36:51], v[168:171], v[220:223], v[36:51]
	global_load_lds_dwordx4 v174, s[96:97]
	s_add_i32 m0, s77, 0xb80
	v_mfma_f32_32x32x16_bf16 v[36:51], v[164:167], v[224:227], v[36:51]
	v_mfma_f32_32x32x16_bf16 v[36:51], v[160:163], v[232:235], v[36:51]
	global_load_lds_dwordx4 v174, s[96:97] offset:128
	v_mfma_f32_32x32x16_bf16 v[36:51], v[156:159], v[236:239], v[36:51]
	s_waitcnt lgkmcnt(0)
	v_mfma_f32_32x32x16_bf16 v[20:35], v[168:171], v[176:179], v[20:35]
	v_mfma_f32_32x32x16_bf16 v[20:35], v[164:167], v[228:231], v[20:35]
	v_mfma_f32_32x32x16_bf16 v[20:35], v[160:163], v[240:243], v[20:35]
	v_mfma_f32_32x32x16_bf16 v[20:35], v[156:159], v[244:247], v[20:35]
	s_branch .LBB0_1034
.Lpa_cons_j0:
	s_xor_b32 s65, s65, 0x4000
	s_xor_b32 s77, s77, 0x8000
	s_add_u32 s74, s74, 0x90000
	s_addc_u32 s75, s75, 0
	s_add_u32 s92, s92, 0x90000
	s_addc_u32 s93, s93, 0
	s_add_u32 s96, s96, 0x90000
	s_addc_u32 s97, s97, 0
	s_mov_b32 m0, s65
	s_nop 0
	global_load_lds_dwordx4 v172, s[74:75]
	s_add_i32 m0, s65, 0x400
	s_nop 0
	global_load_lds_dwordx4 v173, s[74:75]
	s_mov_b32 m0, s77
	s_nop 0
	global_load_lds_dwordx4 v174, s[92:93]
	s_add_i32 m0, s77, 0x380
	s_nop 0
	global_load_lds_dwordx4 v174, s[92:93] offset:128
	s_add_i32 m0, s77, 0x800
	s_nop 0
	global_load_lds_dwordx4 v174, s[96:97]
	s_add_i32 m0, s77, 0xb80
	s_nop 0
	global_load_lds_dwordx4 v174, s[96:97] offset:128
	s_branch .LBB0_1034
